# P0: hand-written workgroup-cooperative weight transposes (64x256 tiles, 1KB row segments, LDS double buffer) + w_r/w_i items spread over workgroups
# speedup vs baseline: 1.0375x; 1.0140x over previous
; #define LAS __attribute__((address_space(3)))
; #define PHASE_BEGIN() P.reload(launder_s(kargs)); const int G = sopq(G0), bx = sopq(bx0); const int lane = opq(lane_id()); const int gw = bx * 8 + wave, NGW = G * 8; (void)gw; (void)NGW; (void)lane
; #define PHASE_BEGIN() P.reload(launder_s(kargs)); const int G = sopq(G0), bx = sopq(bx0); const int lane = opq(lane_id()); const int gw = bx * 8 + wave, NGW = G * 8; (void)gw; (void)NGW; (void)lane
; __global__ void __launch_bounds__(NTHR, 2) fwd_kernel(Args args) {
;     ...
;     if (IN(0)) for (int rep0 = 0; rep0 < REP_P0; ++rep0) {
;         PHASE_BEGIN();
;         LAS float* scr = (LAS float*)(lds + wave * 16640);
;         for (int l = 0; l < DEPTH; ++l) {
;             { const float* wl = P.w_in + (size_t)l * DM * NIN; const float* ng = P.norm_g + l * DM;
;               unsigned char* w8 = P.WIN8() + (size_t)l * N8 * DM; bf16_t* wb = P.WINB() + (size_t)l * NB16 * DM;
;               transpose_matrix<true>(wl + 2048, DM, 4608, NIN, w8, ng, 64.f, scr, gw, NGW, lane);
;               transpose_matrix<true>(wl + 8704, DM, 6144, NIN, w8 + (size_t)4608 * DM, ng, 64.f, scr, gw, NGW, lane);
;               transpose_matrix(wl, DM, 2048, NIN, wb, ng, 1.f, scr, gw, NGW, lane);
;               transpose_matrix(wl + 6656, DM, 2048, NIN, wb + (size_t)2048 * DM, ng, 1.f, scr, gw, NGW, lane); }
;             for (int z = 0; z < 2; ++z) transpose_matrix<true>(P.w_br + (size_t)(l * 3 + z) * 1024 * DM, 1024, DM, DM, P.WBR8() + (size_t)(l * 2 + z) * DM * 1024, nullptr, 32.f, scr, gw, NGW, lane);
;             transpose_matrix(P.w_br + (size_t)(l * 3 + 2) * 1024 * DM, 1024, DM, DM, P.WBR() + (size_t)(l * 3 + 2) * DM * 1024, nullptr, 1.f, scr, gw, NGW, lane);
;             transpose_matrix(P.w_out + (size_t)l * DM * DM, DM, DM, DM, P.WOUT() + (size_t)l * DM * DM, nullptr, 1.f, scr, gw, NGW, lane);
;             transpose_matrix(P.w_pg + (size_t)l * DM * DM, DM, DM, DM, P.WPG() + (size_t)l * DM * DM, P.ple_g + l * DM, 1.f, scr, gw, NGW, lane);
;             transpose_matrix(P.w_pp + (size_t)l * PLE * DM, PLE, DM, DM, P.WPP() + (size_t)l * DM * PLE, nullptr, 1.f, scr, gw, NGW, lane);
.LBB0_19:
	v_readlane_b32 s0, v254, 9
	s_lshr_b32 s0, s0, 6
	s_mov_b32 s49, 0
	v_writelane_b32 v254, s0, 15
	s_nop 0
	v_readlane_b32 s0, v254, 0
	v_readlane_b32 s2, v254, 2
	v_readlane_b32 s1, v254, 1
	v_readlane_b32 s3, v254, 3
	s_cmp_lt_i32 s2, 1
	s_cselect_b64 s[0:1], -1, 0
	s_cmp_gt_i32 s3, 0
	s_cselect_b64 s[2:3], -1, 0
	s_and_b64 s[0:1], s[0:1], s[2:3]
	v_writelane_b32 v254, s0, 16
	s_andn2_b64 vcc, exec, s[0:1]
	s_nop 0
	v_writelane_b32 v254, s1, 17
	s_cbranch_vccnz .LBB0_525
	v_readlane_b32 s0, v254, 7
	v_readlane_b32 s1, v254, 8
	v_readlane_b32 s18, v254, 15
	v_readlane_b32 s19, v254, 4
	s_nop 4
	s_load_dwordx2 s[2:3], s[0:1], 0x20
	s_load_dwordx2 s[4:5], s[0:1], 0x68
	s_load_dwordx2 s[6:7], s[0:1], 0x70
	s_load_dwordx2 s[8:9], s[0:1], 0x80
	s_load_dwordx2 s[10:11], s[0:1], 0x88
	s_load_dwordx2 s[12:13], s[0:1], 0x18
	s_load_dwordx2 s[14:15], s[0:1], 0x78
	s_load_dwordx2 s[16:17], s[0:1], 0xa0
	v_mbcnt_lo_u32_b32 v0, -1, 0
	v_mbcnt_hi_u32_b32 v0, -1, v0
	v_lshlrev_b32_e32 v1, 2, v0
	v_mul_u32_u24_e32 v2, 0x48, v0
	v_mul_u32_u24_e32 v3, 0x90, v0
	s_lshl_b32 s76, s18, 3
	v_add_u32_e32 v2, s76, v2
	s_lshl_b32 s76, s18, 4
	v_add_u32_e32 v3, s76, v3
	s_lshl_b32 s76, s18, 5
	v_lshrrev_b32_e32 v6, 2, v0
	v_add_u32_e32 v6, s76, v6
	v_and_b32_e32 v7, 3, v0
	v_lshlrev_b32_e32 v7, 4, v7
	v_mul_u32_u24_e32 v4, 0x48, v6
	v_add_u32_e32 v4, v4, v7
	v_lshrrev_b32_e32 v8, 3, v0
	v_add_u32_e32 v8, s76, v8
	v_and_b32_e32 v9, 7, v0
	v_lshlrev_b32_e32 v9, 4, v9
	v_mul_u32_u24_e32 v5, 0x90, v8
	v_add_u32_e32 v5, v5, v9
	s_mov_b32 s20, s79
	s_mov_b32 s21, 0
	s_mov_b32 s22, 0
	s_waitcnt lgkmcnt(0)
.Lwt_loop:
	s_cmp_lt_u32 s20, 5568
	s_cselect_b32 s46, 1, 0
	s_cbranch_scc0 .Lwt_setup_done
	s_cmp_ge_u32 s20, 2784
	s_cselect_b32 s68, 1, 0
	s_mul_i32 s76, s68, 2784
	s_sub_u32 s69, s20, s76
	s_cmp_lt_u32 s69, 576
	s_cbranch_scc0 .Lwt_j1
	s_sub_u32 s70, s69, 0
	s_mov_b64 s[88:89], s[2:3]
	s_mov_b32 s90, 0x7400000
	s_mov_b32 s91, 0x2000
	s_mov_b32 s44, 0xe800
	s_mov_b32 s92, 0x0
	s_mov_b32 s93, 0x1500000
	s_mov_b32 s33, 0x800
	s_mov_b32 s29, 0
	s_mov_b64 s[94:95], s[12:13]
	s_mov_b32 s34, 0x42800000
	s_mov_b32 s96, 3641
	s_mov_b32 s97, 18
	s_branch .Lwt_jcommon
.Lwt_j1:
	s_cmp_lt_u32 s69, 1344
	s_cbranch_scc0 .Lwt_j2
	s_sub_u32 s70, s69, 576
	s_mov_b64 s[88:89], s[2:3]
	s_mov_b32 s90, 0x7400000
	s_mov_b32 s91, 0x8800
	s_mov_b32 s44, 0xe800
	s_mov_b32 s92, 0x900000
	s_mov_b32 s93, 0x1500000
	s_mov_b32 s33, 0x800
	s_mov_b32 s29, 0
	s_mov_b64 s[94:95], s[12:13]
	s_mov_b32 s34, 0x42800000
	s_mov_b32 s96, 2731
	s_mov_b32 s97, 24
	s_branch .Lwt_jcommon
.Lwt_j2:
	s_cmp_lt_u32 s69, 1600
	s_cbranch_scc0 .Lwt_j3
	s_sub_u32 s70, s69, 1344
	s_mov_b64 s[88:89], s[2:3]
	s_mov_b32 s90, 0x7400000
	s_mov_b32 s91, 0x0
	s_mov_b32 s44, 0xe800
	s_mov_b32 s92, 0x2a00000
	s_mov_b32 s93, 0x1000000
	s_mov_b32 s33, 0x1000
	s_mov_b32 s29, 1
	s_mov_b64 s[94:95], s[12:13]
	s_mov_b32 s34, 0x3f800000
	s_mov_b32 s96, 8192
	s_mov_b32 s97, 8
	s_branch .Lwt_jcommon
.Lwt_j3:
	s_cmp_lt_u32 s69, 1856
	s_cbranch_scc0 .Lwt_j4
	s_sub_u32 s70, s69, 1600
	s_mov_b64 s[88:89], s[2:3]
	s_mov_b32 s90, 0x7400000
	s_mov_b32 s91, 0x6800
	s_mov_b32 s44, 0xe800
	s_mov_b32 s92, 0x3200000
	s_mov_b32 s93, 0x1000000
	s_mov_b32 s33, 0x1000
	s_mov_b32 s29, 1
	s_mov_b64 s[94:95], s[12:13]
	s_mov_b32 s34, 0x3f800000
	s_mov_b32 s96, 8192
	s_mov_b32 s97, 8
	s_branch .Lwt_jcommon
.Lwt_j4:
	s_cmp_lt_u32 s69, 1984
	s_cbranch_scc0 .Lwt_j5
	s_sub_u32 s70, s69, 1856
	s_mov_b64 s[88:89], s[4:5]
	s_mov_b32 s90, 0x1800000
	s_mov_b32 s91, 0x0
	s_mov_b32 s44, 0x2000
	s_mov_b32 s92, 0x6a00000
	s_mov_b32 s93, 0x400000
	s_mov_b32 s33, 0x400
	s_mov_b32 s29, 0
	s_mov_b64 s[94:95], 0
	s_mov_b32 s34, 0x42000000
	s_mov_b32 s96, 8192
	s_mov_b32 s97, 8
	s_branch .Lwt_jcommon
.Lwt_j5:
	s_cmp_lt_u32 s69, 2112
	s_cbranch_scc0 .Lwt_j6
	s_sub_u32 s70, s69, 1984
	s_mov_b64 s[88:89], s[4:5]
	s_mov_b32 s90, 0x1800000
	s_mov_b32 s91, 0x800000
	s_mov_b32 s44, 0x2000
	s_mov_b32 s92, 0x6c00000
	s_mov_b32 s93, 0x400000
	s_mov_b32 s33, 0x400
	s_mov_b32 s29, 0
	s_mov_b64 s[94:95], 0
	s_mov_b32 s34, 0x42000000
	s_mov_b32 s96, 8192
	s_mov_b32 s97, 8
	s_branch .Lwt_jcommon
.Lwt_j6:
	s_cmp_lt_u32 s69, 2240
	s_cbranch_scc0 .Lwt_j7
	s_sub_u32 s70, s69, 2112
	s_mov_b64 s[88:89], s[4:5]
	s_mov_b32 s90, 0x1800000
	s_mov_b32 s91, 0x1000000
	s_mov_b32 s44, 0x2000
	s_mov_b32 s92, 0x7c00000
	s_mov_b32 s93, 0xc00000
	s_mov_b32 s33, 0x800
	s_mov_b32 s29, 1
	s_mov_b64 s[94:95], 0
	s_mov_b32 s34, 0x3f800000
	s_mov_b32 s96, 8192
	s_mov_b32 s97, 8
	s_branch .Lwt_jcommon
.Lwt_j7:
	s_cmp_lt_u32 s69, 2496
	s_cbranch_scc0 .Lwt_j8
	s_sub_u32 s70, s69, 2240
	s_mov_b64 s[88:89], s[6:7]
	s_mov_b32 s90, 0x1000000
	s_mov_b32 s91, 0x0
	s_mov_b32 s44, 0x2000
	s_mov_b32 s92, 0x8c00000
	s_mov_b32 s93, 0x800000
	s_mov_b32 s33, 0x1000
	s_mov_b32 s29, 1
	s_mov_b64 s[94:95], 0
	s_mov_b32 s34, 0x3f800000
	s_mov_b32 s96, 8192
	s_mov_b32 s97, 8
	s_branch .Lwt_jcommon
.Lwt_j8:
	s_cmp_lt_u32 s69, 2752
	s_cbranch_scc0 .Lwt_j9
	s_sub_u32 s70, s69, 2496
	s_mov_b64 s[88:89], s[8:9]
	s_mov_b32 s90, 0x1000000
	s_mov_b32 s91, 0x0
	s_mov_b32 s44, 0x2000
	s_mov_b32 s92, 0x9c00000
	s_mov_b32 s93, 0x800000
	s_mov_b32 s33, 0x1000
	s_mov_b32 s29, 1
	s_mov_b64 s[94:95], s[14:15]
	s_mov_b32 s34, 0x3f800000
	s_mov_b32 s96, 8192
	s_mov_b32 s97, 8
	s_branch .Lwt_jcommon
.Lwt_j9:
	s_sub_u32 s70, s69, 2752
	s_mov_b64 s[88:89], s[10:11]
	s_mov_b32 s90, 0x200000
	s_mov_b32 s91, 0x0
	s_mov_b32 s44, 0x2000
	s_mov_b32 s92, 0xac00000
	s_mov_b32 s93, 0x100000
	s_mov_b32 s33, 0x200
	s_mov_b32 s29, 1
	s_mov_b64 s[94:95], 0
	s_mov_b32 s34, 0x3f800000
	s_mov_b32 s96, 8192
	s_mov_b32 s97, 8
; #define LAS __attribute__((address_space(3)))
; template <bool F8> __device__ __forceinline__ void transpose_item(const float* W, int K, int N, int ld, void* WTv, const float* kscale, float wscale, LAS float* scr, int item, int lane_) {
;     ...
;     const int nblk = N / 64, kb = item / nblk, nb = item % nblk, k0 = 64 * kb, n0 = 64 * nb;
;     float v[64];
; #pragma unroll
;     for (int kk = 0; kk < 64; ++kk) v[kk] = W[(size_t)(k0 + kk) * ld + n0 + lane];
; #pragma unroll
;     for (int kk = 0; kk < 64; ++kk) { const float sc = (kscale ? kscale[k0 + kk] : 1.f) * wscale; scr[kk * 65 + lane] = v[kk] * sc; }
;     if constexpr (F8) {
;         unsigned char* WT = (unsigned char*)WTv; const int c = lane & 3;
; #pragma unroll
;         for (int j = 0; j < 4; ++j) { const int n = (lane >> 2) + 16 * j; const LAS float* s = scr + (16 * c) * 65 + n; int q[4];
; #pragma unroll
;             for (int d = 0; d < 4; ++d) { int w = 0; w = __builtin_amdgcn_cvt_pk_fp8_f32(s[(4 * d) * 65], s[(4 * d + 1) * 65], w, false); w = __builtin_amdgcn_cvt_pk_fp8_f32(s[(4 * d + 2) * 65], s[(4 * d + 3) * 65], w, true); q[d] = w; }
;             *(u32x4*)(WT + (size_t)(n0 + n) * K + k0 + 16 * c) = (u32x4){(unsigned)q[0], (unsigned)q[1], (unsigned)q[2], (unsigned)q[3]}; }
.Lwt_jcommon:
	s_mul_i32 s73, s70, s96
	s_lshr_b32 s73, s73, 16
	s_mul_i32 s76, s73, s97
	s_sub_u32 s74, s70, s76
	s_lshl_b32 s75, s73, 6
	s_lshl_b32 s76, s18, 3
	s_add_u32 s75, s75, s76
	s_mul_i32 s76, s75, s44
	s_lshl_b32 s77, s74, 10
	s_add_u32 s76, s76, s77
	s_add_u32 s76, s76, s91
	s_mul_i32 s77, s68, s90
	s_add_u32 s76, s76, s77
	s_add_u32 s42, s88, s76
	s_addc_u32 s43, s89, 0
	s_cmp_lg_u64 s[94:95], 0
	s_cselect_b32 s45, 1, 0
	s_lshl_b32 s76, s75, 2
	s_lshl_b32 s77, s68, 13
	s_add_u32 s76, s76, s77
	s_add_u32 s40, s94, s76
	s_addc_u32 s41, s95, 0
	s_lshl_b32 s76, s74, 8
	s_mul_i32 s76, s76, s33
	s_lshl_b32 s77, s73, 6
	s_lshl_b32 s77, s77, s29
	s_add_u32 s76, s76, s77
	s_add_u32 s76, s76, s92
	s_mul_i32 s77, s68, s93
	s_add_u32 s76, s76, s77
	s_add_u32 s30, s16, s76
	s_addc_u32 s31, s17, 0
.Lwt_setup_done:
	s_cmp_eq_u32 s21, 0
	s_cbranch_scc1 .Lwt_issue
	s_waitcnt vmcnt(0) lgkmcnt(0)
	s_mov_b32 s80, s60
	s_mov_b32 s81, s61
	s_mov_b32 s82, s62
	s_mov_b32 s83, s63
	s_mov_b32 s84, s64
	s_mov_b32 s85, s65
	s_mov_b32 s86, s66
	s_mov_b32 s87, s67
	v_mov_b32_e32 v145, s28
	v_mul_f32_e32 v28, s80, v145
	v_mul_f32_e32 v29, s81, v145
	v_mul_f32_e32 v30, s82, v145
	v_mul_f32_e32 v31, s83, v145
	v_mul_f32_e32 v32, s84, v145
	v_mul_f32_e32 v33, s85, v145
	v_mul_f32_e32 v34, s86, v145
	v_mul_f32_e32 v35, s87, v145
	v_mul_f32_e32 v72, v28, v40
	v_mul_f32_e32 v73, v28, v41
	v_mul_f32_e32 v74, v28, v42
	v_mul_f32_e32 v75, v28, v43
	v_mul_f32_e32 v76, v29, v44
	v_mul_f32_e32 v77, v29, v45
	v_mul_f32_e32 v78, v29, v46
	v_mul_f32_e32 v79, v29, v47
	v_mul_f32_e32 v80, v30, v48
	v_mul_f32_e32 v81, v30, v49
	v_mul_f32_e32 v82, v30, v50
	v_mul_f32_e32 v83, v30, v51
	v_mul_f32_e32 v84, v31, v52
	v_mul_f32_e32 v85, v31, v53
	v_mul_f32_e32 v86, v31, v54
	v_mul_f32_e32 v87, v31, v55
	v_mul_f32_e32 v88, v32, v56
	v_mul_f32_e32 v89, v32, v57
	v_mul_f32_e32 v90, v32, v58
	v_mul_f32_e32 v91, v32, v59
	v_mul_f32_e32 v92, v33, v60
	v_mul_f32_e32 v93, v33, v61
	v_mul_f32_e32 v94, v33, v62
	v_mul_f32_e32 v95, v33, v63
	v_mul_f32_e32 v96, v34, v64
	v_mul_f32_e32 v97, v34, v65
	v_mul_f32_e32 v98, v34, v66
	v_mul_f32_e32 v99, v34, v67
	v_mul_f32_e32 v100, v35, v68
	v_mul_f32_e32 v101, v35, v69
	v_mul_f32_e32 v102, v35, v70
	v_mul_f32_e32 v103, v35, v71
.Lwt_issue:
	s_cmp_eq_u32 s46, 0
	s_cbranch_scc1 .Lwt_issued
	v_mov_b32_e32 v20, v1
	v_add_u32_e32 v21, s44, v20
	v_add_u32_e32 v22, s44, v21
	v_add_u32_e32 v23, s44, v22
	v_add_u32_e32 v24, s44, v23
	v_add_u32_e32 v25, s44, v24
	v_add_u32_e32 v26, s44, v25
	v_add_u32_e32 v27, s44, v26
	global_load_dword v40, v20, s[42:43]
	global_load_dword v41, v20, s[42:43] offset:256
	global_load_dword v42, v20, s[42:43] offset:512
	global_load_dword v43, v20, s[42:43] offset:768
	global_load_dword v44, v21, s[42:43]
	global_load_dword v45, v21, s[42:43] offset:256
	global_load_dword v46, v21, s[42:43] offset:512
	global_load_dword v47, v21, s[42:43] offset:768
	global_load_dword v48, v22, s[42:43]
	global_load_dword v49, v22, s[42:43] offset:256
	global_load_dword v50, v22, s[42:43] offset:512
	global_load_dword v51, v22, s[42:43] offset:768
	global_load_dword v52, v23, s[42:43]
	global_load_dword v53, v23, s[42:43] offset:256
	global_load_dword v54, v23, s[42:43] offset:512
	global_load_dword v55, v23, s[42:43] offset:768
	global_load_dword v56, v24, s[42:43]
	global_load_dword v57, v24, s[42:43] offset:256
	global_load_dword v58, v24, s[42:43] offset:512
	global_load_dword v59, v24, s[42:43] offset:768
	global_load_dword v60, v25, s[42:43]
	global_load_dword v61, v25, s[42:43] offset:256
	global_load_dword v62, v25, s[42:43] offset:512
	global_load_dword v63, v25, s[42:43] offset:768
	global_load_dword v64, v26, s[42:43]
	global_load_dword v65, v26, s[42:43] offset:256
	global_load_dword v66, v26, s[42:43] offset:512
	global_load_dword v67, v26, s[42:43] offset:768
	global_load_dword v68, v27, s[42:43]
	global_load_dword v69, v27, s[42:43] offset:256
	global_load_dword v70, v27, s[42:43] offset:512
	global_load_dword v71, v27, s[42:43] offset:768
	s_cmp_eq_u32 s45, 0
	s_cbranch_scc1 .Lwt_noks
	s_load_dwordx8 s[60:67], s[40:41], 0x0
	s_branch .Lwt_issued
.Lwt_noks:
	s_mov_b32 s60, 1.0
	s_mov_b32 s61, 1.0
	s_mov_b32 s62, 1.0
	s_mov_b32 s63, 1.0
	s_mov_b32 s64, 1.0
	s_mov_b32 s65, 1.0
	s_mov_b32 s66, 1.0
	s_mov_b32 s67, 1.0
.Lwt_issued:
	s_cmp_eq_u32 s21, 0
	s_cbranch_scc1 .Lwt_rotate
	v_add_u32_e32 v140, s22, v2
	v_add_u32_e32 v141, s22, v3
	v_add_u32_e32 v142, s22, v4
	v_add_u32_e32 v143, s22, v5
	s_cmp_eq_u32 s23, 0
	s_cbranch_scc0 .Lwt_cvt16
	v_cvt_pk_fp8_f32 v104, v72, v76
	v_cvt_pk_fp8_f32 v105, v88, v92
	v_cvt_pk_fp8_f32 v104, v80, v84 op_sel:[0,0,1]
	v_cvt_pk_fp8_f32 v105, v96, v100 op_sel:[0,0,1]
	v_cvt_pk_fp8_f32 v106, v73, v77
	v_cvt_pk_fp8_f32 v107, v89, v93
	v_cvt_pk_fp8_f32 v106, v81, v85 op_sel:[0,0,1]
	v_cvt_pk_fp8_f32 v107, v97, v101 op_sel:[0,0,1]
	v_cvt_pk_fp8_f32 v108, v74, v78
	v_cvt_pk_fp8_f32 v109, v90, v94
	v_cvt_pk_fp8_f32 v108, v82, v86 op_sel:[0,0,1]
	v_cvt_pk_fp8_f32 v109, v98, v102 op_sel:[0,0,1]
	v_cvt_pk_fp8_f32 v110, v75, v79
	v_cvt_pk_fp8_f32 v111, v91, v95
	v_cvt_pk_fp8_f32 v110, v83, v87 op_sel:[0,0,1]
	v_cvt_pk_fp8_f32 v111, v99, v103 op_sel:[0,0,1]
	s_nop 0
	ds_write_b64 v140, v[104:105]
	s_nop 0
	ds_write_b64 v140, v[106:107] offset:4608
	s_nop 0
	ds_write_b64 v140, v[108:109] offset:9216
	s_nop 0
	ds_write_b64 v140, v[110:111] offset:13824
	s_waitcnt lgkmcnt(0)
	s_barrier
	ds_read_b64 v[120:121], v142
	ds_read_b64 v[122:123], v142 offset:8
	ds_read_b64 v[124:125], v142 offset:1152
	ds_read_b64 v[126:127], v142 offset:1160
	v_mad_u32_u24 v136, v6, s27, v7
	s_lshl_b32 s76, s27, 4
	v_add_u32_e32 v137, s76, v136
	s_waitcnt lgkmcnt(0)
	global_store_dwordx4 v136, v[120:123], s[24:25]
	global_store_dwordx4 v137, v[124:127], s[24:25]
	s_branch .Lwt_rotate
; #define LAS __attribute__((address_space(3)))
; __device__ __forceinline__ unsigned pk2(float lo, float hi) { f32x2 v = {lo, hi}; bf16x2_t b = __builtin_convertvector(v, bf16x2_t); return __builtin_bit_cast(unsigned, b); }
; template <bool F8> __device__ __forceinline__ void transpose_item(const float* W, int K, int N, int ld, void* WTv, const float* kscale, float wscale, LAS float* scr, int item, int lane_) {
;     ...
;     } else {
;         bf16_t* WT = (bf16_t*)WTv; const int c = lane & 7;
; #pragma unroll
;         for (int j = 0; j < 8; ++j) { const int n = (lane >> 3) + 8 * j; const LAS float* s = scr + (8 * c) * 65 + n;
;             u32x4 o; o.x = pk2(s[0 * 65], s[1 * 65]); o.y = pk2(s[2 * 65], s[3 * 65]); o.z = pk2(s[4 * 65], s[5 * 65]); o.w = pk2(s[6 * 65], s[7 * 65]);
;             *(u32x4*)(WT + (size_t)(n0 + n) * K + k0 + 8 * c) = o; }
;     }
; }
; template <bool F8 = false> __device__ __forceinline__ void transpose_matrix(const float* W, int K, int N, int ld, void* WT, const float* kscale, float wscale, LAS float* scr, int gw, int NGW, int lane) {
;     const int nitems = (K / 64) * (N / 64);
;     for (int it = gw; it < nitems; it += NGW) transpose_item<F8>(W, K, N, ld, WT, kscale, wscale, scr, it, lane);
.Lwt_cvt16:
	v_cvt_pk_bf16_f32 v104, v72, v76
	v_cvt_pk_bf16_f32 v105, v80, v84
	v_cvt_pk_bf16_f32 v106, v88, v92
	v_cvt_pk_bf16_f32 v107, v96, v100
	v_cvt_pk_bf16_f32 v108, v73, v77
	v_cvt_pk_bf16_f32 v109, v81, v85
	v_cvt_pk_bf16_f32 v110, v89, v93
	v_cvt_pk_bf16_f32 v111, v97, v101
	v_cvt_pk_bf16_f32 v112, v74, v78
	v_cvt_pk_bf16_f32 v113, v82, v86
	v_cvt_pk_bf16_f32 v114, v90, v94
	v_cvt_pk_bf16_f32 v115, v98, v102
	v_cvt_pk_bf16_f32 v116, v75, v79
	v_cvt_pk_bf16_f32 v117, v83, v87
	v_cvt_pk_bf16_f32 v118, v91, v95
	v_cvt_pk_bf16_f32 v119, v99, v103
	ds_write_b128 v141, v[104:107]
	ds_write_b128 v141, v[108:111] offset:9216
	ds_write_b128 v141, v[112:115] offset:18432
	ds_write_b128 v141, v[116:119] offset:27648
	s_waitcnt lgkmcnt(0)
	s_barrier
	ds_read_b128 v[120:123], v143
	ds_read_b128 v[124:127], v143 offset:1152
	ds_read_b128 v[128:131], v143 offset:2304
	ds_read_b128 v[132:135], v143 offset:3456
	v_mad_u32_u24 v136, v8, s27, v9
	s_lshl_b32 s76, s27, 3
	v_add_u32_e32 v137, s76, v136
	v_add_u32_e32 v138, s76, v137
	v_add_u32_e32 v139, s76, v138
	s_waitcnt lgkmcnt(0)
	global_store_dwordx4 v136, v[120:123], s[24:25]
	global_store_dwordx4 v137, v[124:127], s[24:25]
	global_store_dwordx4 v138, v[128:131], s[24:25]
	global_store_dwordx4 v139, v[132:135], s[24:25]
.Lwt_rotate:
	s_mov_b32 s23, s29
	s_mov_b64 s[24:25], s[30:31]
	s_mov_b32 s27, s33
	s_mov_b32 s28, s34
	s_xor_b32 s22, s22, 0x9000
	s_mov_b32 s21, s46
	s_add_u32 s20, s20, s19
	s_cmp_lg_u32 s21, 0
	s_cbranch_scc1 .Lwt_loop
	s_waitcnt vmcnt(0) lgkmcnt(0)
	s_barrier
	v_readlane_b32 s2, v254, 15
	s_mul_i32 s0, s2, 0x4100
	s_add_i32 s29, s0, 0
	v_readlane_b32 s0, v254, 7
	v_readlane_b32 s1, v254, 8
	s_load_dwordx4 s[4:7], s[0:1], 0x0
	s_mov_b32 s8, s79
	v_mbcnt_lo_u32_b32 v0, -1, 0
	v_mbcnt_hi_u32_b32 v17, -1, v0
	v_mov_b32_e32 v18, v17
	s_waitcnt lgkmcnt(0)
	v_writelane_b32 v254, s4, 18
	v_mov_b32_e32 v21, 0
	v_mov_b32_e32 v90, 0xe800
	v_writelane_b32 v254, s5, 19
	v_writelane_b32 v254, s6, 20
	v_writelane_b32 v254, s7, 21
	s_load_dwordx4 s[12:15], s[0:1], 0x18
	s_load_dwordx2 s[4:5], s[0:1], 0x40
	v_mov_b32_e32 v23, 0x42800000
	s_waitcnt lgkmcnt(0)
	v_writelane_b32 v254, s4, 22
	s_nop 1
	v_writelane_b32 v254, s5, 23
	s_load_dwordx2 s[4:5], s[0:1], 0x50
	s_waitcnt lgkmcnt(0)
	v_writelane_b32 v254, s4, 24
	s_nop 1
	v_writelane_b32 v254, s5, 25
	s_load_dwordx8 s[16:23], s[0:1], 0x68
	s_load_dwordx2 s[4:5], s[0:1], 0x88
	s_waitcnt lgkmcnt(0)
	v_writelane_b32 v254, s4, 26
	s_nop 1
	v_writelane_b32 v254, s5, 27
	s_load_dwordx2 s[4:5], s[0:1], 0xa0
	v_readlane_b32 s0, v254, 4
	s_mov_b32 s6, s0
	v_readlane_b32 s1, v254, 5
	v_writelane_b32 v254, s79, 28
	s_mov_b32 s0, s8
	v_writelane_b32 v254, s0, 29
	s_lshl_b32 s46, s6, 3
	s_mov_b64 s[78:79], -1
	v_writelane_b32 v254, s1, 30
	s_lshl_b32 s0, s8, 3
	s_add_i32 s2, s0, s2
	s_waitcnt lgkmcnt(0)
	s_add_u32 s0, s4, 0x2a00000
	v_writelane_b32 v254, s0, 31
	s_addc_u32 s0, s5, 0
	s_cmpk_lt_i32 s2, 0x900
	v_writelane_b32 v254, s0, 32
	s_cselect_b64 s[0:1], -1, 0
	v_writelane_b32 v254, s0, 33
	s_nop 1
	v_writelane_b32 v254, s1, 34
	v_writelane_b32 v254, s12, 35
	s_cmp_lg_u64 s[12:13], 0
	s_cselect_b64 s[24:25], -1, 0
	v_writelane_b32 v254, s13, 36
	v_writelane_b32 v254, s14, 37
	s_cmpk_lt_i32 s2, 0xc00
	v_writelane_b32 v254, s15, 38
	s_cselect_b64 s[0:1], -1, 0
	v_writelane_b32 v254, s0, 39
	s_cmpk_lt_i32 s2, 0x400
	v_cndmask_b32_e64 v19, 0, 1, s[24:25]
	v_writelane_b32 v254, s1, 40
	s_cselect_b64 s[0:1], -1, 0
	v_writelane_b32 v254, s0, 41
	s_nop 1
	v_writelane_b32 v254, s1, 42
	s_add_u32 s0, s4, 0x6a00000
	v_writelane_b32 v254, s0, 43
	s_addc_u32 s0, s5, 0
	s_cmpk_lt_i32 s2, 0x200
	v_writelane_b32 v254, s0, 44
	s_cselect_b64 s[0:1], -1, 0
	v_writelane_b32 v254, s0, 45
	s_nop 1
	v_writelane_b32 v254, s1, 46
	s_add_u32 s0, s4, 0x7400000
	v_writelane_b32 v254, s0, 47
	s_addc_u32 s0, s5, 0
	v_writelane_b32 v254, s0, 48
	s_add_u32 s0, s4, 0x8c00000
	v_writelane_b32 v254, s0, 49
	s_addc_u32 s0, s5, 0
	v_writelane_b32 v254, s0, 50
	s_add_u32 s0, s4, 0x9c00000
	v_writelane_b32 v254, s0, 51
	s_addc_u32 s0, s5, 0
	v_writelane_b32 v254, s0, 52
	v_writelane_b32 v254, s16, 53
	s_cmp_lg_u64 s[20:21], 0
	s_cselect_b64 s[0:1], -1, 0
	v_writelane_b32 v254, s17, 54
	v_writelane_b32 v254, s18, 55
	v_writelane_b32 v254, s19, 56
	v_writelane_b32 v254, s20, 57
	v_writelane_b32 v254, s21, 58
	v_writelane_b32 v254, s22, 59
	v_writelane_b32 v254, s23, 60
	v_writelane_b32 v254, s0, 61
	s_nop 1
	v_writelane_b32 v254, s1, 62
	s_add_u32 s0, s4, 0xac00000
	v_writelane_b32 v254, s0, 63
	s_addc_u32 s0, s5, 0
	s_cmpk_lt_i32 s2, 0x80
	v_writelane_b32 v255, s0, 0
	s_cselect_b64 s[0:1], -1, 0
	v_writelane_b32 v255, s0, 1
	s_nop 1
	v_writelane_b32 v255, s1, 2
	s_add_u32 s0, s4, 0xae00000
	v_writelane_b32 v255, s0, 3
	s_addc_u32 s0, s5, 0
	s_cmp_lt_i32 s2, 4
	v_writelane_b32 v255, s0, 4
	s_cselect_b64 s[0:1], -1, 0
	v_writelane_b32 v255, s0, 5
	s_nop 1
	v_writelane_b32 v255, s1, 6
	s_add_u32 s0, s4, 0xae80000
	v_writelane_b32 v255, s0, 7
	v_writelane_b32 v255, s4, 8
	s_addc_u32 s0, s5, 0
	s_lshl_b32 s28, s6, 9
	v_writelane_b32 v255, s5, 9
	v_writelane_b32 v255, s0, 10
	s_mov_b32 s0, s6
	v_writelane_b32 v255, s0, 11
	s_nop 1
	v_writelane_b32 v255, s1, 12
	s_mov_b32 s0, s2
	v_writelane_b32 v255, s0, 13
	s_nop 1
	v_writelane_b32 v255, s1, 14
	s_lshl_b32 s0, s2, 6
	v_writelane_b32 v255, s0, 15
	v_writelane_b32 v255, s24, 16
	s_mov_b32 s2, s49
	s_nop 0
	v_writelane_b32 v255, s25, 17
	s_branch .LBB0_22

; __global__ void __launch_bounds__(NTHR, 2) fwd_kernel(Args args) {
;     ...
;             { const float* wl = P.w_in + (size_t)l * DM * NIN; const float* ng = P.norm_g + l * DM;
;               unsigned char* w8 = P.WIN8() + (size_t)l * N8 * DM; bf16_t* wb = P.WINB() + (size_t)l * NB16 * DM;
;               transpose_matrix<true>(wl + 2048, DM, 4608, NIN, w8, ng, 64.f, scr, gw, NGW, lane);
;               transpose_matrix<true>(wl + 8704, DM, 6144, NIN, w8 + (size_t)4608 * DM, ng, 64.f, scr, gw, NGW, lane);
.LBB0_22:
	v_readlane_b32 s4, v254, 35
	s_mul_i32 s0, s2, 0x7400000
	v_readlane_b32 s6, v254, 37
	v_readlane_b32 s7, v254, 38
	s_add_u32 s8, s6, s0
	s_addc_u32 s9, s7, 0
	s_lshl_b32 s48, s2, 11
	s_lshl_b64 s[0:1], s[48:49], 2
	s_add_u32 s6, s4, s0
	v_writelane_b32 v255, s0, 18
	v_readlane_b32 s5, v254, 36
	s_addc_u32 s7, s5, s1
	v_writelane_b32 v255, s1, 19
	s_mov_b32 s18, s2
	s_mul_i32 s0, s2, 0x1500000
	v_readlane_b32 s2, v255, 8
	s_add_u32 s10, s2, s0
	v_readlane_b32 s0, v254, 33
	v_readlane_b32 s3, v255, 9
	v_readlane_b32 s1, v254, 34
	s_addc_u32 s11, s3, 0
	s_andn2_b64 vcc, exec, s[0:1]
	s_branch .LBB0_153
	s_add_u32 s12, s8, 0x2000
	v_readlane_b32 s0, v255, 13
	s_addc_u32 s13, s9, 0
	v_readlane_b32 s14, v255, 15
	s_mov_b32 s15, s0
	v_readlane_b32 s1, v255, 14
	s_branch .LBB0_25

; __global__ void __launch_bounds__(NTHR, 2) fwd_kernel(Args args) {
;     ...
;               transpose_matrix<true>(wl + 8704, DM, 6144, NIN, w8 + (size_t)4608 * DM, ng, 64.f, scr, gw, NGW, lane);
.LBB0_153:
	v_readlane_b32 s0, v254, 39
	v_readlane_b32 s1, v254, 40
	s_andn2_b64 vcc, exec, s[0:1]
	s_branch .LBB0_284
	s_add_u32 s12, s8, 0x8800
	s_addc_u32 s13, s9, 0
	s_add_u32 s10, s10, 0x900000
	v_readlane_b32 s0, v255, 13
	s_addc_u32 s11, s11, 0
	s_lshl_b32 s14, s0, 6
	s_mov_b32 s15, s0
	v_readlane_b32 s1, v255, 14
	s_branch .LBB0_156

; __global__ void __launch_bounds__(NTHR, 2) fwd_kernel(Args args) {
;     ...
;               transpose_matrix(wl, DM, 2048, NIN, wb, ng, 1.f, scr, gw, NGW, lane);
.LBB0_284:
	s_mov_b32 s0, s18
	s_mov_b32 s1, s49
	v_writelane_b32 v255, s0, 20
	v_readlane_b32 s2, v254, 31
	s_nop 0
	v_writelane_b32 v255, s1, 21
	s_lshl_b64 s[0:1], s[0:1], 24
	s_add_u32 s2, s2, s0
	v_readlane_b32 s0, v254, 32
	s_addc_u32 s3, s0, s1
	v_readlane_b32 s0, v254, 41
	v_readlane_b32 s1, v254, 42
	s_andn2_b64 vcc, exec, s[0:1]
	s_nop 0
	v_cndmask_b32_e64 v0, 0, 1, s[0:1]
	v_cmp_ne_u32_e64 s[4:5], 1, v0
	s_nop 1
	v_writelane_b32 v255, s4, 22
	s_nop 1
	v_writelane_b32 v255, s5, 23
	s_branch .LBB0_351
	v_readlane_b32 s0, v255, 13
	s_mov_b32 s4, s0
	s_lshl_b32 s0, s0, 6
	s_or_b32 s10, s0, 56
	s_mov_b32 s11, s4
	v_readlane_b32 s1, v255, 14
	s_branch .LBB0_287

; __global__ void __launch_bounds__(NTHR, 2) fwd_kernel(Args args) {
;     ...
;               transpose_matrix(wl + 6656, DM, 2048, NIN, wb + (size_t)2048 * DM, ng, 1.f, scr, gw, NGW, lane); }
.LBB0_351:
	v_readlane_b32 s0, v255, 22
	v_readlane_b32 s1, v255, 23
	s_and_b64 vcc, exec, s[0:1]
	s_branch .LBB0_418
	s_add_u32 s8, s8, 0x6800
	s_addc_u32 s9, s9, 0
	s_add_u32 s2, s2, 0x800000
	v_readlane_b32 s0, v255, 13
	s_addc_u32 s3, s3, 0
	s_mov_b32 s4, s0
	s_lshl_b32 s0, s0, 6
	s_or_b32 s10, s0, 56
	s_mov_b32 s11, s4
	v_readlane_b32 s1, v255, 14
	s_branch .LBB0_354

; __global__ void __launch_bounds__(NTHR, 2) fwd_kernel(Args args) {
;     ...
;             for (int z = 0; z < 2; ++z) transpose_matrix<true>(P.w_br + (size_t)(l * 3 + z) * 1024 * DM, 1024, DM, DM, P.WBR8() + (size_t)(l * 2 + z) * DM * 1024, nullptr, 32.f, scr, gw, NGW, lane);
.LBB0_419:
	s_xor_b64 s[2:3], s[78:79], -1
	s_mov_b32 s0, 1
	s_mov_b64 s[78:79], 0
	s_and_b64 vcc, exec, s[2:3]
	s_branch .LBB0_423

; __global__ void __launch_bounds__(NTHR, 2) fwd_kernel(Args args) {
;     ...
;             transpose_matrix(P.w_br + (size_t)(l * 3 + 2) * 1024 * DM, 1024, DM, DM, P.WBR() + (size_t)(l * 3 + 2) * DM * 1024, nullptr, 1.f, scr, gw, NGW, lane);
.LBB0_423:
	s_and_b64 vcc, exec, s[4:5]
	s_branch .LBB0_426
	v_readlane_b32 s0, v255, 26
	s_add_i32 s48, s0, 2
	s_lshl_b64 s[0:1], s[48:49], 23
	v_readlane_b32 s4, v254, 53
	v_readlane_b32 s5, v254, 54
	s_add_u32 s33, s4, s0
	s_addc_u32 s45, s5, s1
	s_lshl_b64 s[0:1], s[48:49], 22
	v_readlane_b32 s2, v254, 47
	s_add_u32 s47, s2, s0
	v_readlane_b32 s0, v254, 48
	s_addc_u32 s48, s0, s1
	v_readlane_b32 s0, v255, 13
	s_mov_b32 s2, s0
	s_lshl_b32 s0, s0, 6
	s_or_b32 s58, s0, 56
	s_mov_b32 s59, s2
	v_readlane_b32 s6, v254, 55
	v_readlane_b32 s7, v254, 56
	v_readlane_b32 s8, v254, 57
	v_readlane_b32 s9, v254, 58
	v_readlane_b32 s10, v254, 59
	v_readlane_b32 s11, v254, 60
	v_readlane_b32 s1, v255, 14

; __global__ void __launch_bounds__(NTHR, 2) fwd_kernel(Args args) {
;     ...
;             transpose_matrix(P.w_out + (size_t)l * DM * DM, DM, DM, DM, P.WOUT() + (size_t)l * DM * DM, nullptr, 1.f, scr, gw, NGW, lane);
.LBB0_426:
	v_readlane_b32 s0, v255, 22
	v_readlane_b32 s16, v255, 20
	v_readlane_b32 s1, v255, 23
	v_readlane_b32 s17, v255, 21
	s_and_b64 vcc, exec, s[0:1]
	s_lshl_b64 s[4:5], s[16:17], 22
	s_branch .LBB0_430
	v_readlane_b32 s8, v254, 53
	s_lshl_b64 s[0:1], s[4:5], 2
	v_readlane_b32 s10, v254, 55
	v_readlane_b32 s11, v254, 56
	s_add_u32 s33, s10, s0
	s_addc_u32 s45, s11, s1
	s_lshl_b64 s[0:1], s[4:5], 1
	v_readlane_b32 s2, v254, 49
	s_add_u32 s47, s2, s0
	v_readlane_b32 s0, v254, 50
	s_addc_u32 s48, s0, s1
	v_readlane_b32 s0, v255, 13
	s_mov_b32 s2, s0
	s_lshl_b32 s0, s0, 6
	s_or_b32 s58, s0, 56
	s_mov_b32 s59, s2
	v_readlane_b32 s9, v254, 54
	v_readlane_b32 s12, v254, 57
	v_readlane_b32 s13, v254, 58
	v_readlane_b32 s14, v254, 59
	v_readlane_b32 s15, v254, 60
	v_readlane_b32 s1, v255, 14

; __global__ void __launch_bounds__(NTHR, 2) fwd_kernel(Args args) {
;     ...
;             transpose_matrix(P.w_pg + (size_t)l * DM * DM, DM, DM, DM, P.WPG() + (size_t)l * DM * DM, P.ple_g + l * DM, 1.f, scr, gw, NGW, lane);
.LBB0_430:
	v_readlane_b32 s0, v255, 22
	v_readlane_b32 s1, v255, 23
	s_and_b64 vcc, exec, s[0:1]
	s_branch .LBB0_497
	v_readlane_b32 s8, v254, 53
	s_lshl_b64 s[0:1], s[4:5], 2
	v_readlane_b32 s14, v254, 59
	v_readlane_b32 s15, v254, 60
	s_add_u32 s6, s14, s0
	s_addc_u32 s7, s15, s1
	s_lshl_b64 s[0:1], s[4:5], 1
	v_readlane_b32 s2, v254, 51
	v_readlane_b32 s9, v254, 54
	s_add_u32 s8, s2, s0
	v_readlane_b32 s0, v254, 52
	v_readlane_b32 s10, v254, 55
	v_readlane_b32 s12, v254, 57
	s_addc_u32 s9, s0, s1
	v_readlane_b32 s0, v255, 18
	v_readlane_b32 s11, v254, 56
	v_readlane_b32 s13, v254, 58
	v_readlane_b32 s1, v255, 19
	s_add_u32 s10, s12, s0
	s_addc_u32 s11, s13, s1
	v_readlane_b32 s0, v255, 13
	s_mov_b32 s2, s0
	s_lshl_b32 s0, s0, 6
	s_or_b32 s12, s0, 56
	s_mov_b32 s13, s2
	v_readlane_b32 s1, v255, 14
	s_branch .LBB0_433

; __global__ void __launch_bounds__(NTHR, 2) fwd_kernel(Args args) {
;     ...
;             transpose_matrix(P.w_pp + (size_t)l * PLE * DM, PLE, DM, DM, P.WPP() + (size_t)l * DM * PLE, nullptr, 1.f, scr, gw, NGW, lane);
.LBB0_497:
	v_readlane_b32 s0, v255, 1
	v_readlane_b32 s1, v255, 2
	s_andn2_b64 vcc, exec, s[0:1]
	s_branch .LBB0_501
	s_lshl_b64 s[0:1], s[16:17], 21
	v_readlane_b32 s2, v254, 26
	v_readlane_b32 s3, v254, 27
	s_add_u32 s33, s2, s0
	s_addc_u32 s45, s3, s1
	s_lshl_b64 s[0:1], s[16:17], 20
	v_readlane_b32 s2, v254, 63
	s_add_u32 s47, s2, s0
	v_readlane_b32 s0, v255, 0
	s_addc_u32 s48, s0, s1
	v_readlane_b32 s0, v255, 13
	s_mov_b32 s2, s0
	s_lshl_b32 s0, s0, 6
	s_or_b32 s58, s0, 56
	s_mov_b32 s59, s2
	v_readlane_b32 s1, v255, 14

; __global__ void __launch_bounds__(NTHR, 2) fwd_kernel(Args args) {
;     ...
;             for (int n = 0; n < 8; ++n) {
;                 transpose_matrix(P.w_r + (size_t)(l * 8 + n) * 16384, 128, 128, 128, P.WR() + (size_t)(l * 8 + n) * 16384, nullptr, 1.f, scr, gw, NGW, lane);
;                 transpose_matrix(P.w_i + (size_t)(l * 8 + n) * 16384, 128, 128, 128, P.WI() + (size_t)(l * 8 + n) * 16384, nullptr, 1.f, scr, gw, NGW, lane);
.LBB0_503:
	v_readlane_b32 s0, v255, 13
	s_lshr_b32 s1, s92, 11
	s_lshl_b32 s95, s93, 3
	s_add_u32 s1, s1, s95
	s_sub_u32 s95, s0, s1
	s_cmp_gt_u32 s95, 7
	s_cbranch_scc1 .LBB0_502
	s_lshl_b32 s0, s93, 14
	s_add_i32 s48, s0, s92
	s_lshl_b64 s[2:3], s[48:49], 2
	v_readlane_b32 s0, v254, 22
	v_readlane_b32 s1, v254, 23
	s_add_u32 s33, s0, s2
	s_addc_u32 s45, s1, s3
	s_lshl_b32 s0, s48, 1
	v_readlane_b32 s1, v255, 3
	s_add_u32 s47, s1, s0
	v_readlane_b32 s0, v255, 4
	s_addc_u32 s58, s0, 0
	s_mov_b32 s0, s95
	s_mov_b32 s4, s0
	s_lshl_b32 s0, s0, 6
	s_or_b32 s94, s0, 56
	s_mov_b32 s59, s94
	s_mov_b32 s64, s4
	v_readlane_b32 s1, v255, 14
	s_cmp_gt_u32 s95, 3
	s_cbranch_scc1 .Lwri_skip_r

; __global__ void __launch_bounds__(NTHR, 2) fwd_kernel(Args args) {
;     ...
;                 transpose_matrix(P.w_i + (size_t)(l * 8 + n) * 16384, 128, 128, 128, P.WI() + (size_t)(l * 8 + n) * 16384, nullptr, 1.f, scr, gw, NGW, lane);
.Lwri_skip_r:
	v_readlane_b32 s0, v254, 24
	v_readlane_b32 s1, v254, 25
	s_add_u32 s33, s0, s2
	s_addc_u32 s45, s1, s3
	s_lshl_b32 s0, s48, 1
	v_readlane_b32 s1, v255, 7
	s_add_u32 s47, s1, s0
	v_readlane_b32 s0, v255, 10
	s_addc_u32 s48, s0, 0
	s_sub_u32 s0, s95, 4
	s_mov_b32 s58, s0
	s_lshl_b32 s1, s0, 6
	s_or_b32 s94, s1, 56
	v_readlane_b32 s1, v255, 14
	s_cmp_lt_u32 s95, 4
	s_cbranch_scc1 .LBB0_502
